# P8 HID stores with sc0 nt cache policy
# baseline (speedup 1.0000x reference)
.LBB0_877:
	s_cmp_eq_u32 s100, 0
	s_cbranch_scc1 .Ldhs8_idle
	s_cmp_lt_i32 s61, 6
	s_cbranch_scc0 .Ldhs8_hi
	s_cmp_lt_i32 s61, 2
	s_cbranch_scc0 .Ldhs8_q1
	s_cmp_lt_i32 s61, 0
	s_cbranch_scc0 .Ldhs8_g9
	global_store_dwordx4 v255, v[226:229], s[16:17] sc0 nt
	s_branch .Ldhs8_done
.Ldhs8_g9:
	global_store_dwordx4 v255, v[230:233], s[18:19] sc0 nt
	s_branch .Ldhs8_done
.Ldhs8_q1:
	s_cmp_lt_i32 s61, 4
	s_cbranch_scc0 .Ldhs8_g11
	global_store_dwordx4 v255, v[234:237], s[16:17] offset:1024 sc0 nt
	s_branch .Ldhs8_done
.Ldhs8_g11:
	global_store_dwordx4 v255, v[238:241], s[18:19] offset:1024 sc0 nt
	s_branch .Ldhs8_done
.Ldhs8_hi:
	s_cmp_lt_i32 s61, 10
	s_cbranch_scc0 .Ldhs8_q3
	s_cmp_lt_i32 s61, 8
	s_cbranch_scc0 .Ldhs8_g13
	global_store_dwordx4 v255, v[242:245], s[16:17] offset:2048 sc0 nt
	s_branch .Ldhs8_done
.Ldhs8_g13:
	global_store_dwordx4 v255, v[246:249], s[18:19] offset:2048 sc0 nt
	s_branch .Ldhs8_done
.Ldhs8_q3:
	s_cmp_lt_i32 s61, 12
	s_cbranch_scc0 .Ldhs8_g15
	global_store_dwordx4 v255, v[250:253], s[16:17] offset:3072 sc0 nt
	s_branch .Ldhs8_done
.Ldhs8_g15:
	global_store_dwordx4 v255, v[140:143], s[18:19] offset:3072 sc0 nt
	s_branch .Ldhs8_done

.LBB0_880:
	v_lshl_add_u32 v150, s34, 8, v144
	v_lshl_or_b32 v152, s56, 8, v146
	v_ashrrev_i32_e32 v151, 31, v150
	v_max_f32_e32 v124, 0, v124
	v_max_f32_e32 v120, 0, v120
	v_max_f32_e32 v125, 0, v125
	v_max_f32_e32 v121, 0, v121
	v_max_f32_e32 v126, 0, v126
	v_max_f32_e32 v127, 0, v127
	v_ashrrev_i32_e32 v153, 31, v152
	v_lshlrev_b64 v[154:155], 6, v[150:151]
	v_pk_mul_f32 v[124:125], v[124:125], v[124:125]
	v_pk_mul_f32 v[120:121], v[120:121], v[120:121]
	v_max_f32_e32 v122, 0, v122
	v_max_f32_e32 v123, 0, v123
	v_pk_mul_f32 v[126:127], v[126:127], v[126:127]
	v_pk_mul_f32 v[156:157], v[122:123], v[122:123]
	v_cvt_pk_bf16_f32 v122, v124, v125
	v_cvt_pk_bf16_f32 v123, v126, v127
	v_cvt_pk_bf16_f32 v124, v120, v121
	v_lshl_add_u64 v[120:121], s[78:79], 0, v[154:155]
	v_and_b32_e32 v126, 0xfe0, v152
	v_and_b32_e32 v127, 31, v152
	v_lshlrev_b32_e32 v126, 16, v126
	v_lshl_or_b32 v126, v127, 1, v126
	v_add_u32_e32 v255, v154, v126
	v_mov_b32_e32 v127, 0
	v_cvt_pk_bf16_f32 v125, v156, v157
	v_lshl_add_u64 v[120:121], v[120:121], 0, v[126:127]
	v_max_f32_e32 v112, 0, v112
	v_max_f32_e32 v113, 0, v113
	global_store_dwordx4 v[120:121], v[122:125], off sc0 nt
	s_nop 1
	v_pk_mul_f32 v[122:123], v[112:113], v[112:113]
	v_max_f32_e32 v114, 0, v114
	v_max_f32_e32 v116, 0, v116
	v_max_f32_e32 v117, 0, v117
	v_max_f32_e32 v112, 0, v118
	v_max_f32_e32 v113, 0, v119
	v_max_f32_e32 v115, 0, v115
	v_pk_mul_f32 v[116:117], v[116:117], v[116:117]
	v_pk_mul_f32 v[118:119], v[112:113], v[112:113]
	v_pk_mul_f32 v[124:125], v[114:115], v[114:115]
	v_cvt_pk_bf16_f32 v112, v116, v117
	v_cvt_pk_bf16_f32 v113, v118, v119
	v_cvt_pk_bf16_f32 v114, v122, v123
	v_cvt_pk_bf16_f32 v115, v124, v125
	v_max_f32_e32 v104, 0, v104
	v_max_f32_e32 v105, 0, v105
	v_lshl_add_u64 v[200:201], v[120:121], 0, s[98:99]
	global_store_dwordx4 v[200:201], v[112:115], off sc0 nt
	s_nop 1
	v_or_b32_e32 v112, 16, v150
	v_pk_mul_f32 v[114:115], v[104:105], v[104:105]
	v_ashrrev_i32_e32 v113, 31, v112
	v_max_f32_e32 v108, 0, v108
	v_max_f32_e32 v109, 0, v109
	v_max_f32_e32 v106, 0, v106
	v_lshlrev_b64 v[112:113], 6, v[112:113]
	v_pk_mul_f32 v[108:109], v[108:109], v[108:109]
	v_max_f32_e32 v104, 0, v110
	v_max_f32_e32 v105, 0, v111
	v_max_f32_e32 v107, 0, v107
	v_pk_mul_f32 v[110:111], v[104:105], v[104:105]
	v_pk_mul_f32 v[116:117], v[106:107], v[106:107]
	v_cvt_pk_bf16_f32 v104, v108, v109
	v_lshl_add_u64 v[108:109], s[78:79], 0, v[112:113]
	v_cvt_pk_bf16_f32 v105, v110, v111
	v_cvt_pk_bf16_f32 v106, v114, v115
	v_cvt_pk_bf16_f32 v107, v116, v117
	v_lshl_add_u64 v[108:109], v[108:109], 0, v[126:127]
	v_max_f32_e32 v96, 0, v96
	v_max_f32_e32 v97, 0, v97
	global_store_dwordx4 v[108:109], v[104:107], off sc0 nt
	s_nop 1
	v_pk_mul_f32 v[104:105], v[96:97], v[96:97]
	v_max_f32_e32 v98, 0, v98
	v_max_f32_e32 v100, 0, v100
	v_max_f32_e32 v101, 0, v101
	v_max_f32_e32 v96, 0, v102
	v_max_f32_e32 v97, 0, v103
	v_max_f32_e32 v99, 0, v99
	v_pk_mul_f32 v[100:101], v[100:101], v[100:101]
	v_pk_mul_f32 v[102:103], v[96:97], v[96:97]
	v_pk_mul_f32 v[106:107], v[98:99], v[98:99]
	v_cvt_pk_bf16_f32 v96, v100, v101
	v_cvt_pk_bf16_f32 v97, v102, v103
	v_cvt_pk_bf16_f32 v98, v104, v105
	v_cvt_pk_bf16_f32 v99, v106, v107
	v_max_f32_e32 v88, 0, v88
	v_max_f32_e32 v89, 0, v89
	v_lshl_add_u64 v[202:203], v[108:109], 0, s[98:99]
	global_store_dwordx4 v[202:203], v[96:99], off sc0 nt
	s_nop 1
	v_or_b32_e32 v96, 32, v150
	v_pk_mul_f32 v[98:99], v[88:89], v[88:89]
	v_ashrrev_i32_e32 v97, 31, v96
	v_max_f32_e32 v92, 0, v92
	v_max_f32_e32 v93, 0, v93
	v_max_f32_e32 v90, 0, v90
	v_lshlrev_b64 v[96:97], 6, v[96:97]
	v_pk_mul_f32 v[92:93], v[92:93], v[92:93]
	v_max_f32_e32 v88, 0, v94
	v_max_f32_e32 v89, 0, v95
	v_max_f32_e32 v91, 0, v91
	v_pk_mul_f32 v[94:95], v[88:89], v[88:89]
	v_pk_mul_f32 v[100:101], v[90:91], v[90:91]
	v_cvt_pk_bf16_f32 v88, v92, v93
	v_lshl_add_u64 v[92:93], s[78:79], 0, v[96:97]
	v_cvt_pk_bf16_f32 v89, v94, v95
	v_cvt_pk_bf16_f32 v90, v98, v99
	v_cvt_pk_bf16_f32 v91, v100, v101
	v_lshl_add_u64 v[92:93], v[92:93], 0, v[126:127]
	v_max_f32_e32 v80, 0, v80
	v_max_f32_e32 v81, 0, v81
	global_store_dwordx4 v[92:93], v[88:91], off sc0 nt
	s_nop 1
	v_pk_mul_f32 v[88:89], v[80:81], v[80:81]
	v_max_f32_e32 v82, 0, v82
	v_max_f32_e32 v84, 0, v84
	v_max_f32_e32 v85, 0, v85
	v_max_f32_e32 v80, 0, v86
	v_max_f32_e32 v81, 0, v87
	v_max_f32_e32 v83, 0, v83
	v_pk_mul_f32 v[84:85], v[84:85], v[84:85]
	v_pk_mul_f32 v[86:87], v[80:81], v[80:81]
	v_pk_mul_f32 v[90:91], v[82:83], v[82:83]
	v_cvt_pk_bf16_f32 v80, v84, v85
	v_cvt_pk_bf16_f32 v81, v86, v87
	v_cvt_pk_bf16_f32 v82, v88, v89
	v_cvt_pk_bf16_f32 v83, v90, v91
	v_max_f32_e32 v72, 0, v72
	v_max_f32_e32 v73, 0, v73
	v_lshl_add_u64 v[204:205], v[92:93], 0, s[98:99]
	global_store_dwordx4 v[204:205], v[80:83], off sc0 nt
	s_nop 1
	v_or_b32_e32 v80, 48, v150
	v_pk_mul_f32 v[82:83], v[72:73], v[72:73]
	v_ashrrev_i32_e32 v81, 31, v80
	v_max_f32_e32 v76, 0, v76
	v_max_f32_e32 v77, 0, v77
	v_max_f32_e32 v74, 0, v74
	v_lshlrev_b64 v[80:81], 6, v[80:81]
	v_pk_mul_f32 v[76:77], v[76:77], v[76:77]
	v_max_f32_e32 v72, 0, v78
	v_max_f32_e32 v73, 0, v79
	v_max_f32_e32 v75, 0, v75
	v_pk_mul_f32 v[78:79], v[72:73], v[72:73]
	v_pk_mul_f32 v[84:85], v[74:75], v[74:75]
	v_cvt_pk_bf16_f32 v72, v76, v77
	v_lshl_add_u64 v[76:77], s[78:79], 0, v[80:81]
	v_cvt_pk_bf16_f32 v73, v78, v79
	v_cvt_pk_bf16_f32 v74, v82, v83
	v_cvt_pk_bf16_f32 v75, v84, v85
	v_lshl_add_u64 v[76:77], v[76:77], 0, v[126:127]
	v_max_f32_e32 v64, 0, v64
	v_max_f32_e32 v65, 0, v65
	global_store_dwordx4 v[76:77], v[72:75], off sc0 nt
	s_nop 1
	v_pk_mul_f32 v[72:73], v[64:65], v[64:65]
	v_max_f32_e32 v66, 0, v66
	v_max_f32_e32 v68, 0, v68
	v_max_f32_e32 v69, 0, v69
	v_max_f32_e32 v64, 0, v70
	v_max_f32_e32 v65, 0, v71
	v_max_f32_e32 v67, 0, v67
	v_pk_mul_f32 v[68:69], v[68:69], v[68:69]
	v_pk_mul_f32 v[70:71], v[64:65], v[64:65]
	v_pk_mul_f32 v[74:75], v[66:67], v[66:67]
	v_cvt_pk_bf16_f32 v64, v68, v69
	v_cvt_pk_bf16_f32 v65, v70, v71
	v_cvt_pk_bf16_f32 v66, v72, v73
	v_cvt_pk_bf16_f32 v67, v74, v75
	v_max_f32_e32 v56, 0, v56
	v_max_f32_e32 v57, 0, v57
	v_lshl_add_u64 v[206:207], v[76:77], 0, s[98:99]
	global_store_dwordx4 v[206:207], v[64:67], off sc0 nt
	s_nop 1
	v_pk_mul_f32 v[64:65], v[56:57], v[56:57]
	v_max_f32_e32 v58, 0, v58
	v_max_f32_e32 v56, 0, v62
	v_max_f32_e32 v57, 0, v63
	v_max_f32_e32 v60, 0, v60
	v_max_f32_e32 v61, 0, v61
	v_max_f32_e32 v59, 0, v59
	v_pk_mul_f32 v[62:63], v[56:57], v[56:57]
	v_pk_mul_f32 v[60:61], v[60:61], v[60:61]
	v_pk_mul_f32 v[66:67], v[58:59], v[58:59]
	v_cvt_pk_bf16_f32 v227, v62, v63
	v_cvt_pk_bf16_f32 v226, v60, v61
	v_cvt_pk_bf16_f32 v228, v64, v65
	v_cvt_pk_bf16_f32 v229, v66, v67
	v_max_f32_e32 v48, 0, v48
	v_max_f32_e32 v49, 0, v49
	v_pk_mul_f32 v[56:57], v[48:49], v[48:49]
	v_max_f32_e32 v50, 0, v50
	v_max_f32_e32 v52, 0, v52
	v_max_f32_e32 v53, 0, v53
	v_max_f32_e32 v48, 0, v54
	v_max_f32_e32 v49, 0, v55
	v_max_f32_e32 v51, 0, v51
	v_pk_mul_f32 v[52:53], v[52:53], v[52:53]
	v_pk_mul_f32 v[54:55], v[48:49], v[48:49]
	v_pk_mul_f32 v[58:59], v[50:51], v[50:51]
	v_cvt_pk_bf16_f32 v230, v52, v53
	v_cvt_pk_bf16_f32 v231, v54, v55
	v_cvt_pk_bf16_f32 v232, v56, v57
	v_cvt_pk_bf16_f32 v233, v58, v59
	v_max_f32_e32 v40, 0, v40
	v_max_f32_e32 v41, 0, v41
	v_pk_mul_f32 v[48:49], v[40:41], v[40:41]
	v_max_f32_e32 v42, 0, v42
	v_max_f32_e32 v40, 0, v46
	v_max_f32_e32 v41, 0, v47
	v_max_f32_e32 v44, 0, v44
	v_max_f32_e32 v45, 0, v45
	v_max_f32_e32 v43, 0, v43
	v_pk_mul_f32 v[46:47], v[40:41], v[40:41]
	v_pk_mul_f32 v[44:45], v[44:45], v[44:45]
	v_pk_mul_f32 v[50:51], v[42:43], v[42:43]
	v_cvt_pk_bf16_f32 v235, v46, v47
	v_cvt_pk_bf16_f32 v234, v44, v45
	v_cvt_pk_bf16_f32 v236, v48, v49
	v_cvt_pk_bf16_f32 v237, v50, v51
	v_max_f32_e32 v32, 0, v32
	v_max_f32_e32 v33, 0, v33
	v_pk_mul_f32 v[40:41], v[32:33], v[32:33]
	v_max_f32_e32 v34, 0, v34
	v_max_f32_e32 v36, 0, v36
	v_max_f32_e32 v37, 0, v37
	v_max_f32_e32 v32, 0, v38
	v_max_f32_e32 v33, 0, v39
	v_max_f32_e32 v35, 0, v35
	v_pk_mul_f32 v[36:37], v[36:37], v[36:37]
	v_pk_mul_f32 v[38:39], v[32:33], v[32:33]
	v_pk_mul_f32 v[42:43], v[34:35], v[34:35]
	v_cvt_pk_bf16_f32 v238, v36, v37
	v_cvt_pk_bf16_f32 v239, v38, v39
	v_cvt_pk_bf16_f32 v240, v40, v41
	v_cvt_pk_bf16_f32 v241, v42, v43
	v_max_f32_e32 v24, 0, v24
	v_max_f32_e32 v25, 0, v25
	v_pk_mul_f32 v[32:33], v[24:25], v[24:25]
	v_max_f32_e32 v26, 0, v26
	v_max_f32_e32 v24, 0, v30
	v_max_f32_e32 v25, 0, v31
	v_max_f32_e32 v28, 0, v28
	v_max_f32_e32 v29, 0, v29
	v_max_f32_e32 v27, 0, v27
	v_pk_mul_f32 v[30:31], v[24:25], v[24:25]
	v_pk_mul_f32 v[28:29], v[28:29], v[28:29]
	v_pk_mul_f32 v[34:35], v[26:27], v[26:27]
	v_cvt_pk_bf16_f32 v243, v30, v31
	v_cvt_pk_bf16_f32 v242, v28, v29
	v_cvt_pk_bf16_f32 v244, v32, v33
	v_cvt_pk_bf16_f32 v245, v34, v35
	v_max_f32_e32 v16, 0, v16
	v_max_f32_e32 v17, 0, v17
	v_pk_mul_f32 v[24:25], v[16:17], v[16:17]
	v_max_f32_e32 v18, 0, v18
	v_max_f32_e32 v20, 0, v20
	v_max_f32_e32 v21, 0, v21
	v_max_f32_e32 v16, 0, v22
	v_max_f32_e32 v17, 0, v23
	v_max_f32_e32 v19, 0, v19
	v_pk_mul_f32 v[20:21], v[20:21], v[20:21]
	v_pk_mul_f32 v[22:23], v[16:17], v[16:17]
	v_pk_mul_f32 v[26:27], v[18:19], v[18:19]
	v_cvt_pk_bf16_f32 v246, v20, v21
	v_cvt_pk_bf16_f32 v247, v22, v23
	v_cvt_pk_bf16_f32 v248, v24, v25
	v_cvt_pk_bf16_f32 v249, v26, v27
	v_max_f32_e32 v8, 0, v8
	v_max_f32_e32 v9, 0, v9
	v_pk_mul_f32 v[16:17], v[8:9], v[8:9]
	v_max_f32_e32 v10, 0, v10
	v_max_f32_e32 v8, 0, v14
	v_max_f32_e32 v9, 0, v15
	v_max_f32_e32 v12, 0, v12
	v_max_f32_e32 v13, 0, v13
	v_max_f32_e32 v11, 0, v11
	v_pk_mul_f32 v[14:15], v[8:9], v[8:9]
	v_pk_mul_f32 v[12:13], v[12:13], v[12:13]
	v_pk_mul_f32 v[18:19], v[10:11], v[10:11]
	v_cvt_pk_bf16_f32 v251, v14, v15
	v_cvt_pk_bf16_f32 v250, v12, v13
	v_cvt_pk_bf16_f32 v252, v16, v17
	v_cvt_pk_bf16_f32 v253, v18, v19
	v_max_f32_e32 v0, 0, v0
	v_max_f32_e32 v1, 0, v1
	v_pk_mul_f32 v[8:9], v[0:1], v[0:1]
	v_max_f32_e32 v2, 0, v2
	v_max_f32_e32 v4, 0, v4
	v_max_f32_e32 v5, 0, v5
	v_max_f32_e32 v0, 0, v6
	v_max_f32_e32 v1, 0, v7
	v_max_f32_e32 v3, 0, v3
	v_pk_mul_f32 v[4:5], v[4:5], v[4:5]
	v_pk_mul_f32 v[6:7], v[0:1], v[0:1]
	v_pk_mul_f32 v[10:11], v[2:3], v[2:3]
	v_cvt_pk_bf16_f32 v140, v4, v5
	v_cvt_pk_bf16_f32 v141, v6, v7
	v_cvt_pk_bf16_f32 v142, v8, v9
	v_cvt_pk_bf16_f32 v143, v10, v11
	s_andn2_b64 vcc, exec, s[4:5]
	s_mov_b64 s[4:5], -1
	s_mov_b32 s100, 1
	s_cbranch_vccnz .LBB0_869
	s_andn2_b64 vcc, exec, s[6:7]
	s_cbranch_vccnz .LBB0_868
	s_barrier
	s_branch .LBB0_868
.LBB0_883:
	global_store_dwordx4 v255, v[226:229], s[16:17] sc0 nt
	global_store_dwordx4 v255, v[230:233], s[18:19] sc0 nt
	global_store_dwordx4 v255, v[234:237], s[16:17] offset:1024 sc0 nt
	global_store_dwordx4 v255, v[238:241], s[18:19] offset:1024 sc0 nt
	global_store_dwordx4 v255, v[242:245], s[16:17] offset:2048 sc0 nt
	global_store_dwordx4 v255, v[246:249], s[18:19] offset:2048 sc0 nt
	global_store_dwordx4 v255, v[250:253], s[16:17] offset:3072 sc0 nt
	global_store_dwordx4 v255, v[140:143], s[18:19] offset:3072 sc0 nt
	s_waitcnt vmcnt(0)
	s_barrier
